# PanelRms exchange: each row-statistics slot is stored twice, write-through (sc1, as before) and then as a plain store that keeps the line in the XCD's L2, where the panel's other three column-tile own
# baseline (speedup 1.0000x reference)
;     __device__ __forceinline__ void run(const f32x4 (&v)[2][2][4][2], const Unit& u, int wr, int wc, int fr, int fq, PG8_LAS unsigned char* lds, int wid, int lane) const {
;     ...
;         const int row = wid * 32 + (lane & 31);
;         if (lane < 32) {
;             const float t = (P[row * 4 + 0] + P[row * 4 + 1]) + (P[row * 4 + 2] + P[row * 4 + 3]);
;             __hip_atomic_store(xbuf + ((size_t)(u.pm * BM + row) * 4 + u.pn), t, __ATOMIC_RELAXED, __HIP_MEMORY_SCOPE_AGENT);
;         }
.LBB0_777:
	s_or_b64 exec, exec, s[2:3]
	s_add_u32 s10, s86, 0x2d00000
	s_addc_u32 s11, s87, 0
	s_lshl_b32 s1, s93, 5
	s_waitcnt lgkmcnt(0)
	s_barrier
	v_and_or_b32 v193, v192, 31, s1
	v_add_u32_e32 v214, s16, v193
	v_cmp_gt_i32_e64 s[6:7], 32, v192
	v_lshl_add_u32 v233, v193, 4, 0
	v_ashrrev_i32_e32 v215, 31, v214
	s_and_saveexec_b64 s[2:3], s[6:7]
	s_cbranch_execz .LBB0_779
	s_waitcnt lgkmcnt(0)
	ds_read_b128 v[194:197], v233
	s_ashr_i32 s1, s0, 31
	v_lshl_add_u64 v[198:199], v[214:215], 4, s[10:11]
	s_waitcnt lgkmcnt(0)
	v_mov_b32_e32 v200, v195
	v_mov_b32_e32 v201, v196
	v_mov_b32_e32 v195, v197
	v_pk_add_f32 v[194:195], v[200:201], v[194:195]
	v_lshl_add_u64 v[196:197], s[0:1], 2, v[198:199]
	v_pk_add_f32 v[194:195], v[194:195], v[194:195] op_sel:[0,1] op_sel_hi:[1,0]
	global_store_dword v[196:197], v194, off sc1
	global_store_dword v[196:197], v194, off

;     __device__ __forceinline__ void run(const f32x4 (&v)[2][2][4][2], const Unit& u, int wr, int wc, int fr, int fq, PG8_LAS unsigned char* lds, int wid, int lane) const {
;     ...
;         const int row = wid * 32 + (lane & 31);
;         if (lane < 32) {
;             const float t = (P[row * 4 + 0] + P[row * 4 + 1]) + (P[row * 4 + 2] + P[row * 4 + 3]);
;             __hip_atomic_store(xbuf + ((size_t)(u.pm * BM + row) * 4 + u.pn), t, __ATOMIC_RELAXED, __HIP_MEMORY_SCOPE_AGENT);
;         }
.LBB0_806:
	s_or_b64 exec, exec, s[10:11]
	s_waitcnt lgkmcnt(0)
	s_barrier
	s_add_u32 s4, s86, 0x2d40000
	s_addc_u32 s5, s87, 0
	s_and_saveexec_b64 s[10:11], s[6:7]
	s_cbranch_execz .LBB0_808
	s_waitcnt lgkmcnt(0)
	ds_read_b128 v[134:137], v233
	s_ashr_i32 s1, s0, 31
	v_lshl_add_u64 v[138:139], v[214:215], 4, s[4:5]
	s_waitcnt lgkmcnt(0)
	v_mov_b32_e32 v140, v135
	v_mov_b32_e32 v141, v136
	v_mov_b32_e32 v135, v137
	v_pk_add_f32 v[134:135], v[140:141], v[134:135]
	v_lshl_add_u64 v[136:137], s[0:1], 2, v[138:139]
	v_pk_add_f32 v[134:135], v[134:135], v[134:135] op_sel:[0,1] op_sel_hi:[1,0]
	global_store_dword v[136:137], v134, off sc1
	global_store_dword v[136:137], v134, off

;     __device__ __forceinline__ void run(const f32x4 (&v)[2][2][4][2], const Unit& u, int wr, int wc, int fr, int fq, PG8_LAS unsigned char* lds, int wid, int lane) const {
;     ...
;         const int row = wid * 32 + (lane & 31);
;         if (lane < 32) {
;             const float t = (P[row * 4 + 0] + P[row * 4 + 1]) + (P[row * 4 + 2] + P[row * 4 + 3]);
;             __hip_atomic_store(xbuf + ((size_t)(u.pm * BM + row) * 4 + u.pn), t, __ATOMIC_RELAXED, __HIP_MEMORY_SCOPE_AGENT);
;         }
.LBB0_1807:
	s_or_b64 exec, exec, s[6:7]
	s_add_u32 s12, s86, 0x2d80000
	s_addc_u32 s13, s87, 0
	s_lshl_b32 s3, s93, 5
	s_waitcnt lgkmcnt(0)
	s_barrier
	v_and_or_b32 v128, v148, 31, s3
	v_add_u32_e32 v180, s18, v128
	v_cmp_gt_i32_e64 s[6:7], 32, v148
	v_lshl_add_u32 v189, v128, 4, 0
	v_ashrrev_i32_e32 v181, 31, v180
	s_and_saveexec_b64 s[8:9], s[6:7]
	s_cbranch_execz .LBB0_1809
	ds_read_b128 v[134:137], v189
	s_ashr_i32 s3, s2, 31
	v_lshl_add_u64 v[138:139], v[180:181], 4, s[12:13]
	s_waitcnt lgkmcnt(0)
	v_mov_b32_e32 v140, v135
	v_mov_b32_e32 v141, v136
	v_mov_b32_e32 v135, v137
	v_pk_add_f32 v[134:135], v[140:141], v[134:135]
	v_lshl_add_u64 v[136:137], s[2:3], 2, v[138:139]
	v_pk_add_f32 v[134:135], v[134:135], v[134:135] op_sel:[0,1] op_sel_hi:[1,0]
	global_store_dword v[136:137], v134, off sc1
	global_store_dword v[136:137], v134, off

;     __device__ __forceinline__ void run(const f32x4 (&v)[2][2][4][2], const Unit& u, int wr, int wc, int fr, int fq, PG8_LAS unsigned char* lds, int wid, int lane) const {
;     ...
;         const int row = wid * 32 + (lane & 31);
;         if (lane < 32) {
;             const float t = (P[row * 4 + 0] + P[row * 4 + 1]) + (P[row * 4 + 2] + P[row * 4 + 3]);
;             __hip_atomic_store(xbuf + ((size_t)(u.pm * BM + row) * 4 + u.pn), t, __ATOMIC_RELAXED, __HIP_MEMORY_SCOPE_AGENT);
;         }
.LBB0_1836:
	s_or_b64 exec, exec, s[12:13]
	s_waitcnt lgkmcnt(0)
	s_barrier
	s_add_u32 s4, s86, 0x2dc0000
	s_addc_u32 s5, s87, 0
	s_and_saveexec_b64 s[12:13], s[6:7]
	s_cbranch_execz .LBB0_1838
	s_waitcnt lgkmcnt(0)
	ds_read_b128 v[134:137], v189
	s_ashr_i32 s3, s2, 31
	v_lshl_add_u64 v[138:139], v[180:181], 4, s[4:5]
	s_waitcnt lgkmcnt(0)
	v_mov_b32_e32 v140, v135
	v_mov_b32_e32 v141, v136
	v_mov_b32_e32 v135, v137
	v_pk_add_f32 v[134:135], v[140:141], v[134:135]
	v_lshl_add_u64 v[136:137], s[2:3], 2, v[138:139]
	v_pk_add_f32 v[134:135], v[134:135], v[134:135] op_sel:[0,1] op_sel_hi:[1,0]
	global_store_dword v[136:137], v134, off sc1
	global_store_dword v[136:137], v134, off

;     __device__ __forceinline__ void run(const f32x4 (&v)[2][2][4][2], const Unit& u, int wr, int wc, int fr, int fq, PG8_LAS unsigned char* lds, int wid, int lane) const {
;     ...
;         const int row = wid * 32 + (lane & 31);
;         if (lane < 32) {
;             const float t = (P[row * 4 + 0] + P[row * 4 + 1]) + (P[row * 4 + 2] + P[row * 4 + 3]);
;             __hip_atomic_store(xbuf + ((size_t)(u.pm * BM + row) * 4 + u.pn), t, __ATOMIC_RELAXED, __HIP_MEMORY_SCOPE_AGENT);
;         }
.LBB0_2481:
	s_or_b64 exec, exec, s[0:1]
	s_add_u32 s4, s86, 0x2e00000
	s_addc_u32 s5, s87, 0
	s_lshl_b32 s0, s93, 5
	s_waitcnt lgkmcnt(0)
	s_barrier
	s_waitcnt lgkmcnt(0)
	v_and_or_b32 v167, v166, 31, s0
	v_add_u32_e32 v164, s8, v167
	v_cmp_gt_i32_e64 s[0:1], 32, v166
	v_ashrrev_i32_e32 v165, 31, v164
	s_and_saveexec_b64 s[6:7], s[0:1]
	s_cbranch_execz .LBB0_2483
	v_lshl_add_u32 v168, v167, 4, 0
	ds_read_b128 v[168:171], v168
	s_ashr_i32 s3, s2, 31
	v_lshl_add_u64 v[172:173], v[164:165], 4, s[4:5]
	s_waitcnt lgkmcnt(0)
	v_mov_b32_e32 v174, v169
	v_mov_b32_e32 v175, v170
	v_mov_b32_e32 v169, v171
	v_pk_add_f32 v[168:169], v[174:175], v[168:169]
	v_lshl_add_u64 v[170:171], s[2:3], 2, v[172:173]
	v_pk_add_f32 v[168:169], v[168:169], v[168:169] op_sel:[0,1] op_sel_hi:[1,0]
	global_store_dword v[170:171], v168, off sc1
	global_store_dword v[170:171], v168, off
